# grid barrier: all workgroups wait on the cross-XCD release generation directly; XCD leaders no longer bump/wait on the per-XCD generation word
# speedup vs baseline: 1.0058x; 1.0058x over previous
; __device__ __forceinline__ unsigned xb_ld(unsigned* p)              { return __hip_atomic_load(p, __ATOMIC_RELAXED, __HIP_MEMORY_SCOPE_AGENT); }
; __device__ __forceinline__ unsigned xb_add(unsigned* p, unsigned v) { return __hip_atomic_fetch_add(p, v, __ATOMIC_RELAXED, __HIP_MEMORY_SCOPE_AGENT); }
; #define XB_SPIN(cond, bar) do { unsigned _sp = 0; while (cond) { __builtin_amdgcn_s_sleep(1); \
;     if ((++_sp & 255u) == 0u) { if (xb_ld(&(bar)[XB_TMO])) break; if (_sp > XB_SPIN_CAP) { atomicAdd(&(bar)[XB_TMO], 1u); break; } } } } while (0)
; __device__ __forceinline__ void xcd_barrier(const XcdBarrier& b) {
;     ...
;         const unsigned old = xb_add(&bar[XB_XSUB(b.x)], 1u);
;         const unsigned gen = old / nloc;
;         if (old + 1u == (gen + 1u) * nloc) {
;             __builtin_amdgcn_fence(__ATOMIC_RELEASE, "agent");
;             asm volatile("s_waitcnt vmcnt(0)" ::: "memory");
;             const unsigned og = xb_add(&bar[XB_TOP], 1u);
;             const unsigned tg = og / nx;
;             if (og + 1u == (tg + 1u) * nx) xb_add(&bar[XB_TOPGEN], 1u);
;             else XB_SPIN(xb_ld(&bar[XB_TOPGEN]) == tg, bar);
;             __builtin_amdgcn_fence(__ATOMIC_ACQUIRE, "agent");
;             xb_add(&bar[XB_XGEN(b.x)], 1u);
;             asm volatile("s_waitcnt vmcnt(0)" ::: "memory");
;         } else {
;             XB_SPIN(xb_ld(&bar[XB_XGEN(b.x)]) == gen, bar);
;             __builtin_amdgcn_fence(__ATOMIC_ACQUIRE, "agent");
;             asm volatile("s_waitcnt vmcnt(0)" ::: "memory");
.LBB0_91:
	s_or_b64 exec, exec, s[8:9]
	v_cvt_f32_u32_e32 v4, v2
	s_waitcnt vmcnt(0)
	v_readfirstlane_b32 s3, v3
	v_sub_u32_e32 v3, 0, v2
	v_rcp_iflag_f32_e32 v4, v4
	v_add_u32_e32 v5, s3, v1
	v_mul_f32_e32 v4, 0x4f7ffffe, v4
	v_cvt_u32_f32_e32 v4, v4
	v_mul_lo_u32 v1, v3, v4
	v_mul_hi_u32 v1, v4, v1
	v_add_u32_e32 v1, v4, v1
	v_mul_hi_u32 v1, v5, v1
	v_mul_lo_u32 v3, v1, v2
	v_sub_u32_e32 v3, v5, v3
	v_add_u32_e32 v4, 1, v1
	v_cmp_ge_u32_e32 vcc, v3, v2
	s_nop 1
	v_cndmask_b32_e32 v1, v1, v4, vcc
	v_sub_u32_e32 v4, v3, v2
	v_cndmask_b32_e32 v3, v3, v4, vcc
	v_add_u32_e32 v4, 1, v1
	v_cmp_ge_u32_e32 vcc, v3, v2
	v_add_u32_e32 v3, 1, v5
	s_nop 0
	v_cndmask_b32_e32 v1, v1, v4, vcc
	v_mul_lo_u32 v4, v2, v1
	v_add_u32_e32 v2, v4, v2
	v_cmp_ne_u32_e32 vcc, v3, v2
	s_and_saveexec_b64 s[6:7], vcc
	s_xor_b64 s[6:7], exec, s[6:7]
	s_cbranch_execz .LBB0_105
	s_waitcnt lgkmcnt(0)
	s_add_u32 s38, s26, 0x7500
	s_addc_u32 s39, s27, 0
	v_mov_b32_e32 v0, 0
	global_load_dword v0, v0, s[38:39] sc1
	s_waitcnt vmcnt(0)
	v_cmp_eq_u32_e32 vcc, v0, v1
	s_and_saveexec_b64 s[8:9], vcc
	s_cbranch_execz .LBB0_104
	s_add_u32 s10, s26, 0x4200
	s_addc_u32 s11, s27, 0
	s_mov_b32 s3, 1
	s_mov_b64 s[40:41], 0
	v_mov_b32_e32 v0, 0
	s_branch .LBB0_95

; __device__ __forceinline__ unsigned xb_add(unsigned* p, unsigned v) { return __hip_atomic_fetch_add(p, v, __ATOMIC_RELAXED, __HIP_MEMORY_SCOPE_AGENT); }
; __device__ __forceinline__ void xcd_barrier(const XcdBarrier& b) {
;     ...
;             __builtin_amdgcn_fence(__ATOMIC_ACQUIRE, "agent");
;             xb_add(&bar[XB_XGEN(b.x)], 1u);
;             asm volatile("s_waitcnt vmcnt(0)" ::: "memory");
.LBB0_122:
	s_or_b64 exec, exec, s[6:7]
	s_mov_b64 s[6:7], exec
	v_mbcnt_lo_u32_b32 v0, s6, 0
	v_mbcnt_hi_u32_b32 v0, s7, v0
	v_cmp_eq_u32_e32 vcc, 0, v0
	s_waitcnt vmcnt(0)
	buffer_inv sc1
	s_and_saveexec_b64 s[8:9], vcc
	s_cbranch_execz .LBB0_124
	s_bcnt1_i32_b64 s3, s[6:7]
.LBB0_124:
	s_or_b64 exec, exec, s[8:9]
	s_waitcnt vmcnt(0)

; __device__ __forceinline__ unsigned xb_ld(unsigned* p)              { return __hip_atomic_load(p, __ATOMIC_RELAXED, __HIP_MEMORY_SCOPE_AGENT); }
; __device__ __forceinline__ unsigned xb_add(unsigned* p, unsigned v) { return __hip_atomic_fetch_add(p, v, __ATOMIC_RELAXED, __HIP_MEMORY_SCOPE_AGENT); }
; #define XB_SPIN(cond, bar) do { unsigned _sp = 0; while (cond) { __builtin_amdgcn_s_sleep(1); \
;     if ((++_sp & 255u) == 0u) { if (xb_ld(&(bar)[XB_TMO])) break; if (_sp > XB_SPIN_CAP) { atomicAdd(&(bar)[XB_TMO], 1u); break; } } } } while (0)
; __device__ __forceinline__ void xcd_barrier(const XcdBarrier& b) {
;     ...
;         const unsigned old = xb_add(&bar[XB_XSUB(b.x)], 1u);
;         const unsigned gen = old / nloc;
;         if (old + 1u == (gen + 1u) * nloc) {
;             __builtin_amdgcn_fence(__ATOMIC_RELEASE, "agent");
;             asm volatile("s_waitcnt vmcnt(0)" ::: "memory");
;             const unsigned og = xb_add(&bar[XB_TOP], 1u);
;             const unsigned tg = og / nx;
;             if (og + 1u == (tg + 1u) * nx) xb_add(&bar[XB_TOPGEN], 1u);
;             else XB_SPIN(xb_ld(&bar[XB_TOPGEN]) == tg, bar);
;             __builtin_amdgcn_fence(__ATOMIC_ACQUIRE, "agent");
;             xb_add(&bar[XB_XGEN(b.x)], 1u);
;             asm volatile("s_waitcnt vmcnt(0)" ::: "memory");
;         } else {
;             XB_SPIN(xb_ld(&bar[XB_XGEN(b.x)]) == gen, bar);
;             __builtin_amdgcn_fence(__ATOMIC_ACQUIRE, "agent");
;             asm volatile("s_waitcnt vmcnt(0)" ::: "memory");
.LBB0_801:
	s_or_b64 exec, exec, s[12:13]
	v_cvt_f32_u32_e32 v4, v2
	s_waitcnt vmcnt(0)
	v_readfirstlane_b32 s0, v3
	v_sub_u32_e32 v3, 0, v2
	v_rcp_iflag_f32_e32 v4, v4
	v_add_u32_e32 v5, s0, v1
	v_mul_f32_e32 v4, 0x4f7ffffe, v4
	v_cvt_u32_f32_e32 v4, v4
	v_mul_lo_u32 v1, v3, v4
	v_mul_hi_u32 v1, v4, v1
	v_add_u32_e32 v1, v4, v1
	v_mul_hi_u32 v1, v5, v1
	v_mul_lo_u32 v3, v1, v2
	v_sub_u32_e32 v3, v5, v3
	v_add_u32_e32 v4, 1, v1
	v_cmp_ge_u32_e32 vcc, v3, v2
	s_nop 1
	v_cndmask_b32_e32 v1, v1, v4, vcc
	v_sub_u32_e32 v4, v3, v2
	v_cndmask_b32_e32 v3, v3, v4, vcc
	v_add_u32_e32 v4, 1, v1
	v_cmp_ge_u32_e32 vcc, v3, v2
	v_add_u32_e32 v3, 1, v5
	s_nop 0
	v_cndmask_b32_e32 v1, v1, v4, vcc
	v_mul_lo_u32 v4, v2, v1
	v_add_u32_e32 v2, v4, v2
	v_cmp_ne_u32_e32 vcc, v3, v2
	s_and_saveexec_b64 s[0:1], vcc
	s_xor_b64 s[8:9], exec, s[0:1]
	s_cbranch_execz .LBB0_815
	s_waitcnt lgkmcnt(0)
	s_add_u32 s16, s26, 0x7500
	s_addc_u32 s17, s27, 0
	v_mov_b32_e32 v0, 0
	global_load_dword v0, v0, s[16:17] sc1
	s_waitcnt vmcnt(0)
	v_cmp_eq_u32_e32 vcc, v0, v1
	s_and_saveexec_b64 s[12:13], vcc
	s_cbranch_execz .LBB0_814
	s_add_u32 s14, s26, 0x4200
	s_addc_u32 s15, s27, 0
	s_mov_b32 s0, 1
	s_mov_b64 s[18:19], 0
	v_mov_b32_e32 v0, 0
	s_branch .LBB0_805

; __device__ __forceinline__ unsigned xb_add(unsigned* p, unsigned v) { return __hip_atomic_fetch_add(p, v, __ATOMIC_RELAXED, __HIP_MEMORY_SCOPE_AGENT); }
; __device__ __forceinline__ void xcd_barrier(const XcdBarrier& b) {
;     ...
;             __builtin_amdgcn_fence(__ATOMIC_ACQUIRE, "agent");
;             xb_add(&bar[XB_XGEN(b.x)], 1u);
;             asm volatile("s_waitcnt vmcnt(0)" ::: "memory");
.LBB0_832:
	s_or_b64 exec, exec, s[8:9]
	s_mov_b64 s[8:9], exec
	v_mbcnt_lo_u32_b32 v0, s8, 0
	v_mbcnt_hi_u32_b32 v0, s9, v0
	v_cmp_eq_u32_e32 vcc, 0, v0
	s_waitcnt vmcnt(0)
	buffer_inv sc1
	s_and_saveexec_b64 s[12:13], vcc
	s_cbranch_execz .LBB0_834
	s_bcnt1_i32_b64 s0, s[8:9]
.LBB0_834:
	s_or_b64 exec, exec, s[12:13]
	s_waitcnt vmcnt(0)

; __device__ __forceinline__ unsigned xb_ld(unsigned* p)              { return __hip_atomic_load(p, __ATOMIC_RELAXED, __HIP_MEMORY_SCOPE_AGENT); }
; __device__ __forceinline__ unsigned xb_add(unsigned* p, unsigned v) { return __hip_atomic_fetch_add(p, v, __ATOMIC_RELAXED, __HIP_MEMORY_SCOPE_AGENT); }
; #define XB_SPIN(cond, bar) do { unsigned _sp = 0; while (cond) { __builtin_amdgcn_s_sleep(1); \
;     if ((++_sp & 255u) == 0u) { if (xb_ld(&(bar)[XB_TMO])) break; if (_sp > XB_SPIN_CAP) { atomicAdd(&(bar)[XB_TMO], 1u); break; } } } } while (0)
; __device__ __forceinline__ void xcd_barrier(const XcdBarrier& b) {
;     ...
;         const unsigned old = xb_add(&bar[XB_XSUB(b.x)], 1u);
;         const unsigned gen = old / nloc;
;         if (old + 1u == (gen + 1u) * nloc) {
;             __builtin_amdgcn_fence(__ATOMIC_RELEASE, "agent");
;             asm volatile("s_waitcnt vmcnt(0)" ::: "memory");
;             const unsigned og = xb_add(&bar[XB_TOP], 1u);
;             const unsigned tg = og / nx;
;             if (og + 1u == (tg + 1u) * nx) xb_add(&bar[XB_TOPGEN], 1u);
;             else XB_SPIN(xb_ld(&bar[XB_TOPGEN]) == tg, bar);
;             __builtin_amdgcn_fence(__ATOMIC_ACQUIRE, "agent");
;             xb_add(&bar[XB_XGEN(b.x)], 1u);
;             asm volatile("s_waitcnt vmcnt(0)" ::: "memory");
;         } else {
;             XB_SPIN(xb_ld(&bar[XB_XGEN(b.x)]) == gen, bar);
;             __builtin_amdgcn_fence(__ATOMIC_ACQUIRE, "agent");
;             asm volatile("s_waitcnt vmcnt(0)" ::: "memory");
.LBB0_997:
	s_or_b64 exec, exec, s[10:11]
	v_cvt_f32_u32_e32 v4, v2
	s_waitcnt vmcnt(0)
	v_readfirstlane_b32 s0, v3
	v_sub_u32_e32 v3, 0, v2
	v_rcp_iflag_f32_e32 v4, v4
	v_add_u32_e32 v5, s0, v1
	v_mul_f32_e32 v4, 0x4f7ffffe, v4
	v_cvt_u32_f32_e32 v4, v4
	v_mul_lo_u32 v1, v3, v4
	v_mul_hi_u32 v1, v4, v1
	v_add_u32_e32 v1, v4, v1
	v_mul_hi_u32 v1, v5, v1
	v_mul_lo_u32 v3, v1, v2
	v_sub_u32_e32 v3, v5, v3
	v_add_u32_e32 v4, 1, v1
	v_cmp_ge_u32_e32 vcc, v3, v2
	s_nop 1
	v_cndmask_b32_e32 v1, v1, v4, vcc
	v_sub_u32_e32 v4, v3, v2
	v_cndmask_b32_e32 v3, v3, v4, vcc
	v_add_u32_e32 v4, 1, v1
	v_cmp_ge_u32_e32 vcc, v3, v2
	v_add_u32_e32 v3, 1, v5
	s_nop 0
	v_cndmask_b32_e32 v1, v1, v4, vcc
	v_mul_lo_u32 v4, v2, v1
	v_add_u32_e32 v2, v4, v2
	v_cmp_ne_u32_e32 vcc, v3, v2
	s_and_saveexec_b64 s[0:1], vcc
	s_xor_b64 s[8:9], exec, s[0:1]
	s_cbranch_execz .LBB0_1011
	s_waitcnt lgkmcnt(0)
	s_add_u32 s20, s26, 0x7500
	s_addc_u32 s21, s27, 0
	v_mov_b32_e32 v0, 0
	global_load_dword v0, v0, s[20:21] sc1
	s_waitcnt vmcnt(0)
	v_cmp_eq_u32_e32 vcc, v0, v1
	s_and_saveexec_b64 s[10:11], vcc
	s_cbranch_execz .LBB0_1010
	s_add_u32 s18, s26, 0x4200
	s_addc_u32 s19, s27, 0
	s_mov_b32 s0, 1
	s_mov_b64 s[42:43], 0
	v_mov_b32_e32 v0, 0
	s_branch .LBB0_1001

; __device__ __forceinline__ unsigned xb_add(unsigned* p, unsigned v) { return __hip_atomic_fetch_add(p, v, __ATOMIC_RELAXED, __HIP_MEMORY_SCOPE_AGENT); }
; __device__ __forceinline__ void xcd_barrier(const XcdBarrier& b) {
;     ...
;             __builtin_amdgcn_fence(__ATOMIC_ACQUIRE, "agent");
;             xb_add(&bar[XB_XGEN(b.x)], 1u);
;             asm volatile("s_waitcnt vmcnt(0)" ::: "memory");
.LBB0_1028:
	s_or_b64 exec, exec, s[8:9]
	s_mov_b64 s[8:9], exec
	v_mbcnt_lo_u32_b32 v0, s8, 0
	v_mbcnt_hi_u32_b32 v0, s9, v0
	v_cmp_eq_u32_e32 vcc, 0, v0
	s_waitcnt vmcnt(0)
	buffer_inv sc1
	s_and_saveexec_b64 s[10:11], vcc
	s_cbranch_execz .LBB0_1030
	s_bcnt1_i32_b64 s0, s[8:9]
.LBB0_1030:
	s_or_b64 exec, exec, s[10:11]
	s_waitcnt vmcnt(0)

; __device__ __forceinline__ unsigned xb_ld(unsigned* p)              { return __hip_atomic_load(p, __ATOMIC_RELAXED, __HIP_MEMORY_SCOPE_AGENT); }
; __device__ __forceinline__ unsigned xb_add(unsigned* p, unsigned v) { return __hip_atomic_fetch_add(p, v, __ATOMIC_RELAXED, __HIP_MEMORY_SCOPE_AGENT); }
; #define XB_SPIN(cond, bar) do { unsigned _sp = 0; while (cond) { __builtin_amdgcn_s_sleep(1); \
;     if ((++_sp & 255u) == 0u) { if (xb_ld(&(bar)[XB_TMO])) break; if (_sp > XB_SPIN_CAP) { atomicAdd(&(bar)[XB_TMO], 1u); break; } } } } while (0)
; __device__ __forceinline__ void xcd_barrier(const XcdBarrier& b) {
;     ...
;         const unsigned old = xb_add(&bar[XB_XSUB(b.x)], 1u);
;         const unsigned gen = old / nloc;
;         if (old + 1u == (gen + 1u) * nloc) {
;             __builtin_amdgcn_fence(__ATOMIC_RELEASE, "agent");
;             asm volatile("s_waitcnt vmcnt(0)" ::: "memory");
;             const unsigned og = xb_add(&bar[XB_TOP], 1u);
;             const unsigned tg = og / nx;
;             if (og + 1u == (tg + 1u) * nx) xb_add(&bar[XB_TOPGEN], 1u);
;             else XB_SPIN(xb_ld(&bar[XB_TOPGEN]) == tg, bar);
;             __builtin_amdgcn_fence(__ATOMIC_ACQUIRE, "agent");
;             xb_add(&bar[XB_XGEN(b.x)], 1u);
;             asm volatile("s_waitcnt vmcnt(0)" ::: "memory");
;         } else {
;             XB_SPIN(xb_ld(&bar[XB_XGEN(b.x)]) == gen, bar);
;             __builtin_amdgcn_fence(__ATOMIC_ACQUIRE, "agent");
;             asm volatile("s_waitcnt vmcnt(0)" ::: "memory");
.LBB0_1121:
	s_or_b64 exec, exec, s[16:17]
	v_cvt_f32_u32_e32 v4, v2
	s_waitcnt vmcnt(0)
	v_readfirstlane_b32 s0, v3
	v_sub_u32_e32 v3, 0, v2
	v_rcp_iflag_f32_e32 v4, v4
	v_add_u32_e32 v5, s0, v1
	v_mul_f32_e32 v4, 0x4f7ffffe, v4
	v_cvt_u32_f32_e32 v4, v4
	v_mul_lo_u32 v1, v3, v4
	v_mul_hi_u32 v1, v4, v1
	v_add_u32_e32 v1, v4, v1
	v_mul_hi_u32 v1, v5, v1
	v_mul_lo_u32 v3, v1, v2
	v_sub_u32_e32 v3, v5, v3
	v_add_u32_e32 v4, 1, v1
	v_cmp_ge_u32_e32 vcc, v3, v2
	s_nop 1
	v_cndmask_b32_e32 v1, v1, v4, vcc
	v_sub_u32_e32 v4, v3, v2
	v_cndmask_b32_e32 v3, v3, v4, vcc
	v_add_u32_e32 v4, 1, v1
	v_cmp_ge_u32_e32 vcc, v3, v2
	v_add_u32_e32 v3, 1, v5
	s_nop 0
	v_cndmask_b32_e32 v1, v1, v4, vcc
	v_mul_lo_u32 v4, v2, v1
	v_add_u32_e32 v2, v4, v2
	v_cmp_ne_u32_e32 vcc, v3, v2
	s_and_saveexec_b64 s[0:1], vcc
	s_xor_b64 s[10:11], exec, s[0:1]
	s_cbranch_execz .LBB0_1135
	s_waitcnt lgkmcnt(0)
	s_add_u32 s20, s26, 0x7500
	s_addc_u32 s21, s27, 0
	v_mov_b32_e32 v0, 0
	global_load_dword v0, v0, s[20:21] sc1
	s_waitcnt vmcnt(0)
	v_cmp_eq_u32_e32 vcc, v0, v1
	s_and_saveexec_b64 s[16:17], vcc
	s_cbranch_execz .LBB0_1134
	s_add_u32 s18, s26, 0x4200
	s_addc_u32 s19, s27, 0
	s_mov_b32 s0, 1
	s_mov_b64 s[42:43], 0
	v_mov_b32_e32 v0, 0
	s_branch .LBB0_1125

; __device__ __forceinline__ unsigned xb_add(unsigned* p, unsigned v) { return __hip_atomic_fetch_add(p, v, __ATOMIC_RELAXED, __HIP_MEMORY_SCOPE_AGENT); }
; __device__ __forceinline__ void xcd_barrier(const XcdBarrier& b) {
;     ...
;             __builtin_amdgcn_fence(__ATOMIC_ACQUIRE, "agent");
;             xb_add(&bar[XB_XGEN(b.x)], 1u);
;             asm volatile("s_waitcnt vmcnt(0)" ::: "memory");
.LBB0_1152:
	s_or_b64 exec, exec, s[10:11]
	s_mov_b64 s[10:11], exec
	v_mbcnt_lo_u32_b32 v0, s10, 0
	v_mbcnt_hi_u32_b32 v0, s11, v0
	v_cmp_eq_u32_e32 vcc, 0, v0
	s_waitcnt vmcnt(0)
	buffer_inv sc1
	s_and_saveexec_b64 s[16:17], vcc
	s_cbranch_execz .LBB0_1154
	s_bcnt1_i32_b64 s0, s[10:11]
.LBB0_1154:
	s_or_b64 exec, exec, s[16:17]
	s_waitcnt vmcnt(0)

; __device__ __forceinline__ unsigned xb_add(unsigned* p, unsigned v) { return __hip_atomic_fetch_add(p, v, __ATOMIC_RELAXED, __HIP_MEMORY_SCOPE_AGENT); }
; __device__ __forceinline__ void xcd_barrier(const XcdBarrier& b) {
;     ...
;             __builtin_amdgcn_fence(__ATOMIC_ACQUIRE, "agent");
;             xb_add(&bar[XB_XGEN(b.x)], 1u);
;             asm volatile("s_waitcnt vmcnt(0)" ::: "memory");
.LBB0_1232:
	s_or_b64 exec, exec, s[10:11]
	s_mov_b64 s[10:11], exec
	v_mbcnt_lo_u32_b32 v0, s10, 0
	v_mbcnt_hi_u32_b32 v0, s11, v0
	v_cmp_eq_u32_e32 vcc, 0, v0
	s_waitcnt vmcnt(0)
	buffer_inv sc1
	s_and_saveexec_b64 s[16:17], vcc
	s_cbranch_execz .LBB0_1234
	s_bcnt1_i32_b64 s0, s[10:11]
.LBB0_1234:
	s_or_b64 exec, exec, s[16:17]
	s_waitcnt vmcnt(0)

; __device__ __forceinline__ unsigned xb_ld(unsigned* p)              { return __hip_atomic_load(p, __ATOMIC_RELAXED, __HIP_MEMORY_SCOPE_AGENT); }
; __device__ __forceinline__ unsigned xb_add(unsigned* p, unsigned v) { return __hip_atomic_fetch_add(p, v, __ATOMIC_RELAXED, __HIP_MEMORY_SCOPE_AGENT); }
; #define XB_SPIN(cond, bar) do { unsigned _sp = 0; while (cond) { __builtin_amdgcn_s_sleep(1); \
;     if ((++_sp & 255u) == 0u) { if (xb_ld(&(bar)[XB_TMO])) break; if (_sp > XB_SPIN_CAP) { atomicAdd(&(bar)[XB_TMO], 1u); break; } } } } while (0)
; __device__ __forceinline__ void xcd_barrier(const XcdBarrier& b) {
;     ...
;         const unsigned old = xb_add(&bar[XB_XSUB(b.x)], 1u);
;         const unsigned gen = old / nloc;
;         if (old + 1u == (gen + 1u) * nloc) {
;             __builtin_amdgcn_fence(__ATOMIC_RELEASE, "agent");
;             asm volatile("s_waitcnt vmcnt(0)" ::: "memory");
;             const unsigned og = xb_add(&bar[XB_TOP], 1u);
;             const unsigned tg = og / nx;
;             if (og + 1u == (tg + 1u) * nx) xb_add(&bar[XB_TOPGEN], 1u);
;             else XB_SPIN(xb_ld(&bar[XB_TOPGEN]) == tg, bar);
;             __builtin_amdgcn_fence(__ATOMIC_ACQUIRE, "agent");
;             xb_add(&bar[XB_XGEN(b.x)], 1u);
;             asm volatile("s_waitcnt vmcnt(0)" ::: "memory");
;         } else {
;             XB_SPIN(xb_ld(&bar[XB_XGEN(b.x)]) == gen, bar);
;             __builtin_amdgcn_fence(__ATOMIC_ACQUIRE, "agent");
;             asm volatile("s_waitcnt vmcnt(0)" ::: "memory");
.LBB0_1277:
	s_or_b64 exec, exec, s[10:11]
	v_cvt_f32_u32_e32 v4, v2
	s_waitcnt vmcnt(0)
	v_readfirstlane_b32 s3, v3
	v_sub_u32_e32 v3, 0, v2
	v_rcp_iflag_f32_e32 v4, v4
	v_add_u32_e32 v5, s3, v1
	v_mul_f32_e32 v4, 0x4f7ffffe, v4
	v_cvt_u32_f32_e32 v4, v4
	v_mul_lo_u32 v1, v3, v4
	v_mul_hi_u32 v1, v4, v1
	v_add_u32_e32 v1, v4, v1
	v_mul_hi_u32 v1, v5, v1
	v_mul_lo_u32 v3, v1, v2
	v_sub_u32_e32 v3, v5, v3
	v_add_u32_e32 v4, 1, v1
	v_cmp_ge_u32_e32 vcc, v3, v2
	s_nop 1
	v_cndmask_b32_e32 v1, v1, v4, vcc
	v_sub_u32_e32 v4, v3, v2
	v_cndmask_b32_e32 v3, v3, v4, vcc
	v_add_u32_e32 v4, 1, v1
	v_cmp_ge_u32_e32 vcc, v3, v2
	v_add_u32_e32 v3, 1, v5
	s_nop 0
	v_cndmask_b32_e32 v1, v1, v4, vcc
	v_mul_lo_u32 v4, v2, v1
	v_add_u32_e32 v2, v4, v2
	v_cmp_ne_u32_e32 vcc, v3, v2
	s_and_saveexec_b64 s[8:9], vcc
	s_xor_b64 s[8:9], exec, s[8:9]
	s_cbranch_execz .LBB0_1291
	s_waitcnt lgkmcnt(0)
	s_add_u32 s16, s26, 0x7500
	s_addc_u32 s17, s27, 0
	v_mov_b32_e32 v0, 0
	global_load_dword v0, v0, s[16:17] sc1
	s_waitcnt vmcnt(0)
	v_cmp_eq_u32_e32 vcc, v0, v1
	s_and_saveexec_b64 s[10:11], vcc
	s_cbranch_execz .LBB0_1290
	s_add_u32 s12, s26, 0x4200
	s_addc_u32 s13, s27, 0
	s_mov_b32 s3, 1
	s_mov_b64 s[18:19], 0
	v_mov_b32_e32 v0, 0
	s_branch .LBB0_1281

; __device__ __forceinline__ unsigned xb_add(unsigned* p, unsigned v) { return __hip_atomic_fetch_add(p, v, __ATOMIC_RELAXED, __HIP_MEMORY_SCOPE_AGENT); }
; __device__ __forceinline__ void xcd_barrier(const XcdBarrier& b) {
;     ...
;             __builtin_amdgcn_fence(__ATOMIC_ACQUIRE, "agent");
;             xb_add(&bar[XB_XGEN(b.x)], 1u);
;             asm volatile("s_waitcnt vmcnt(0)" ::: "memory");
.LBB0_1308:
	s_or_b64 exec, exec, s[8:9]
	s_mov_b64 s[8:9], exec
	v_mbcnt_lo_u32_b32 v0, s8, 0
	v_mbcnt_hi_u32_b32 v0, s9, v0
	v_cmp_eq_u32_e32 vcc, 0, v0
	s_waitcnt vmcnt(0)
	buffer_inv sc1
	s_and_saveexec_b64 s[10:11], vcc
	s_cbranch_execz .LBB0_1310
	s_bcnt1_i32_b64 s3, s[8:9]
.LBB0_1310:
	s_or_b64 exec, exec, s[10:11]
	s_waitcnt vmcnt(0)

; __device__ __forceinline__ unsigned xb_ld(unsigned* p)              { return __hip_atomic_load(p, __ATOMIC_RELAXED, __HIP_MEMORY_SCOPE_AGENT); }
; __device__ __forceinline__ unsigned xb_add(unsigned* p, unsigned v) { return __hip_atomic_fetch_add(p, v, __ATOMIC_RELAXED, __HIP_MEMORY_SCOPE_AGENT); }
; #define XB_SPIN(cond, bar) do { unsigned _sp = 0; while (cond) { __builtin_amdgcn_s_sleep(1); \
;     if ((++_sp & 255u) == 0u) { if (xb_ld(&(bar)[XB_TMO])) break; if (_sp > XB_SPIN_CAP) { atomicAdd(&(bar)[XB_TMO], 1u); break; } } } } while (0)
; __device__ __forceinline__ void xcd_barrier(const XcdBarrier& b) {
;     ...
;         const unsigned old = xb_add(&bar[XB_XSUB(b.x)], 1u);
;         const unsigned gen = old / nloc;
;         if (old + 1u == (gen + 1u) * nloc) {
;             __builtin_amdgcn_fence(__ATOMIC_RELEASE, "agent");
;             asm volatile("s_waitcnt vmcnt(0)" ::: "memory");
;             const unsigned og = xb_add(&bar[XB_TOP], 1u);
;             const unsigned tg = og / nx;
;             if (og + 1u == (tg + 1u) * nx) xb_add(&bar[XB_TOPGEN], 1u);
;             else XB_SPIN(xb_ld(&bar[XB_TOPGEN]) == tg, bar);
;             __builtin_amdgcn_fence(__ATOMIC_ACQUIRE, "agent");
;             xb_add(&bar[XB_XGEN(b.x)], 1u);
;             asm volatile("s_waitcnt vmcnt(0)" ::: "memory");
;         } else {
;             XB_SPIN(xb_ld(&bar[XB_XGEN(b.x)]) == gen, bar);
;             __builtin_amdgcn_fence(__ATOMIC_ACQUIRE, "agent");
;             asm volatile("s_waitcnt vmcnt(0)" ::: "memory");
.LBB0_1435:
	s_or_b64 exec, exec, s[12:13]
	v_cvt_f32_u32_e32 v4, v2
	s_waitcnt vmcnt(0)
	v_readfirstlane_b32 s3, v3
	v_sub_u32_e32 v3, 0, v2
	v_rcp_iflag_f32_e32 v4, v4
	v_add_u32_e32 v5, s3, v1
	v_mul_f32_e32 v4, 0x4f7ffffe, v4
	v_cvt_u32_f32_e32 v4, v4
	v_mul_lo_u32 v1, v3, v4
	v_mul_hi_u32 v1, v4, v1
	v_add_u32_e32 v1, v4, v1
	v_mul_hi_u32 v1, v5, v1
	v_mul_lo_u32 v3, v1, v2
	v_sub_u32_e32 v3, v5, v3
	v_add_u32_e32 v4, 1, v1
	v_cmp_ge_u32_e32 vcc, v3, v2
	s_nop 1
	v_cndmask_b32_e32 v1, v1, v4, vcc
	v_sub_u32_e32 v4, v3, v2
	v_cndmask_b32_e32 v3, v3, v4, vcc
	v_add_u32_e32 v4, 1, v1
	v_cmp_ge_u32_e32 vcc, v3, v2
	v_add_u32_e32 v3, 1, v5
	s_nop 0
	v_cndmask_b32_e32 v1, v1, v4, vcc
	v_mul_lo_u32 v4, v2, v1
	v_add_u32_e32 v2, v4, v2
	v_cmp_ne_u32_e32 vcc, v3, v2
	s_and_saveexec_b64 s[10:11], vcc
	s_xor_b64 s[10:11], exec, s[10:11]
	s_cbranch_execz .LBB0_1449
	s_waitcnt lgkmcnt(0)
	s_add_u32 s36, s26, 0x7500
	s_addc_u32 s37, s27, 0
	v_mov_b32_e32 v0, 0
	global_load_dword v0, v0, s[36:37] sc1
	s_waitcnt vmcnt(0)
	v_cmp_eq_u32_e32 vcc, v0, v1
	s_and_saveexec_b64 s[12:13], vcc
	s_cbranch_execz .LBB0_1448
	s_add_u32 s20, s26, 0x4200
	s_addc_u32 s21, s27, 0
	s_mov_b32 s3, 1
	s_mov_b64 s[38:39], 0
	v_mov_b32_e32 v0, 0
	s_branch .LBB0_1439

; __device__ __forceinline__ unsigned xb_add(unsigned* p, unsigned v) { return __hip_atomic_fetch_add(p, v, __ATOMIC_RELAXED, __HIP_MEMORY_SCOPE_AGENT); }
; __device__ __forceinline__ void xcd_barrier(const XcdBarrier& b) {
;     ...
;             __builtin_amdgcn_fence(__ATOMIC_ACQUIRE, "agent");
;             xb_add(&bar[XB_XGEN(b.x)], 1u);
;             asm volatile("s_waitcnt vmcnt(0)" ::: "memory");
.LBB0_1466:
	s_or_b64 exec, exec, s[10:11]
	s_mov_b64 s[10:11], exec
	v_mbcnt_lo_u32_b32 v0, s10, 0
	v_mbcnt_hi_u32_b32 v0, s11, v0
	v_cmp_eq_u32_e32 vcc, 0, v0
	s_waitcnt vmcnt(0)
	buffer_inv sc1
	s_and_saveexec_b64 s[12:13], vcc
	s_cbranch_execz .LBB0_1468
	s_bcnt1_i32_b64 s3, s[10:11]
.LBB0_1468:
	s_or_b64 exec, exec, s[12:13]
	s_waitcnt vmcnt(0)

; __device__ __forceinline__ unsigned xb_ld(unsigned* p)              { return __hip_atomic_load(p, __ATOMIC_RELAXED, __HIP_MEMORY_SCOPE_AGENT); }
; __device__ __forceinline__ unsigned xb_add(unsigned* p, unsigned v) { return __hip_atomic_fetch_add(p, v, __ATOMIC_RELAXED, __HIP_MEMORY_SCOPE_AGENT); }
; #define XB_SPIN(cond, bar) do { unsigned _sp = 0; while (cond) { __builtin_amdgcn_s_sleep(1); \
;     if ((++_sp & 255u) == 0u) { if (xb_ld(&(bar)[XB_TMO])) break; if (_sp > XB_SPIN_CAP) { atomicAdd(&(bar)[XB_TMO], 1u); break; } } } } while (0)
; __device__ __forceinline__ void xcd_barrier(const XcdBarrier& b) {
;     ...
;         const unsigned old = xb_add(&bar[XB_XSUB(b.x)], 1u);
;         const unsigned gen = old / nloc;
;         if (old + 1u == (gen + 1u) * nloc) {
;             __builtin_amdgcn_fence(__ATOMIC_RELEASE, "agent");
;             asm volatile("s_waitcnt vmcnt(0)" ::: "memory");
;             const unsigned og = xb_add(&bar[XB_TOP], 1u);
;             const unsigned tg = og / nx;
;             if (og + 1u == (tg + 1u) * nx) xb_add(&bar[XB_TOPGEN], 1u);
;             else XB_SPIN(xb_ld(&bar[XB_TOPGEN]) == tg, bar);
;             __builtin_amdgcn_fence(__ATOMIC_ACQUIRE, "agent");
;             xb_add(&bar[XB_XGEN(b.x)], 1u);
;             asm volatile("s_waitcnt vmcnt(0)" ::: "memory");
;         } else {
;             XB_SPIN(xb_ld(&bar[XB_XGEN(b.x)]) == gen, bar);
;             __builtin_amdgcn_fence(__ATOMIC_ACQUIRE, "agent");
;             asm volatile("s_waitcnt vmcnt(0)" ::: "memory");
.LBB0_1503:
	s_or_b64 exec, exec, s[12:13]
	v_cvt_f32_u32_e32 v4, v2
	s_waitcnt vmcnt(0)
	v_readfirstlane_b32 s3, v3
	v_sub_u32_e32 v3, 0, v2
	v_rcp_iflag_f32_e32 v4, v4
	v_add_u32_e32 v5, s3, v1
	v_mul_f32_e32 v4, 0x4f7ffffe, v4
	v_cvt_u32_f32_e32 v4, v4
	v_mul_lo_u32 v1, v3, v4
	v_mul_hi_u32 v1, v4, v1
	v_add_u32_e32 v1, v4, v1
	v_mul_hi_u32 v1, v5, v1
	v_mul_lo_u32 v3, v1, v2
	v_sub_u32_e32 v3, v5, v3
	v_add_u32_e32 v4, 1, v1
	v_cmp_ge_u32_e32 vcc, v3, v2
	s_nop 1
	v_cndmask_b32_e32 v1, v1, v4, vcc
	v_sub_u32_e32 v4, v3, v2
	v_cndmask_b32_e32 v3, v3, v4, vcc
	v_add_u32_e32 v4, 1, v1
	v_cmp_ge_u32_e32 vcc, v3, v2
	v_add_u32_e32 v3, 1, v5
	s_nop 0
	v_cndmask_b32_e32 v1, v1, v4, vcc
	v_mul_lo_u32 v4, v2, v1
	v_add_u32_e32 v2, v4, v2
	v_cmp_ne_u32_e32 vcc, v3, v2
	s_and_saveexec_b64 s[10:11], vcc
	s_xor_b64 s[10:11], exec, s[10:11]
	s_cbranch_execz .LBB0_1517
	s_waitcnt lgkmcnt(0)
	s_add_u32 s20, s26, 0x7500
	s_addc_u32 s21, s27, 0
	v_mov_b32_e32 v0, 0
	global_load_dword v0, v0, s[20:21] sc1
	s_waitcnt vmcnt(0)
	v_cmp_eq_u32_e32 vcc, v0, v1
	s_and_saveexec_b64 s[12:13], vcc
	s_cbranch_execz .LBB0_1516
	s_add_u32 s18, s26, 0x4200
	s_addc_u32 s19, s27, 0
	s_mov_b32 s3, 1
	s_mov_b64 s[36:37], 0
	v_mov_b32_e32 v0, 0
	s_branch .LBB0_1507

; __device__ __forceinline__ unsigned xb_add(unsigned* p, unsigned v) { return __hip_atomic_fetch_add(p, v, __ATOMIC_RELAXED, __HIP_MEMORY_SCOPE_AGENT); }
; __device__ __forceinline__ void xcd_barrier(const XcdBarrier& b) {
;     ...
;             __builtin_amdgcn_fence(__ATOMIC_ACQUIRE, "agent");
;             xb_add(&bar[XB_XGEN(b.x)], 1u);
;             asm volatile("s_waitcnt vmcnt(0)" ::: "memory");
.LBB0_1534:
	s_or_b64 exec, exec, s[10:11]
	s_mov_b64 s[10:11], exec
	v_mbcnt_lo_u32_b32 v0, s10, 0
	v_mbcnt_hi_u32_b32 v0, s11, v0
	v_cmp_eq_u32_e32 vcc, 0, v0
	s_waitcnt vmcnt(0)
	buffer_inv sc1
	s_and_saveexec_b64 s[12:13], vcc
	s_cbranch_execz .LBB0_1536
	s_bcnt1_i32_b64 s3, s[10:11]
.LBB0_1536:
	s_or_b64 exec, exec, s[12:13]
	s_waitcnt vmcnt(0)

; __device__ __forceinline__ unsigned xb_ld(unsigned* p)              { return __hip_atomic_load(p, __ATOMIC_RELAXED, __HIP_MEMORY_SCOPE_AGENT); }
; __device__ __forceinline__ unsigned xb_add(unsigned* p, unsigned v) { return __hip_atomic_fetch_add(p, v, __ATOMIC_RELAXED, __HIP_MEMORY_SCOPE_AGENT); }
; #define XB_SPIN(cond, bar) do { unsigned _sp = 0; while (cond) { __builtin_amdgcn_s_sleep(1); \
;     if ((++_sp & 255u) == 0u) { if (xb_ld(&(bar)[XB_TMO])) break; if (_sp > XB_SPIN_CAP) { atomicAdd(&(bar)[XB_TMO], 1u); break; } } } } while (0)
; __device__ __forceinline__ void xcd_barrier(const XcdBarrier& b) {
;     ...
;         const unsigned old = xb_add(&bar[XB_XSUB(b.x)], 1u);
;         const unsigned gen = old / nloc;
;         if (old + 1u == (gen + 1u) * nloc) {
;             __builtin_amdgcn_fence(__ATOMIC_RELEASE, "agent");
;             asm volatile("s_waitcnt vmcnt(0)" ::: "memory");
;             const unsigned og = xb_add(&bar[XB_TOP], 1u);
;             const unsigned tg = og / nx;
;             if (og + 1u == (tg + 1u) * nx) xb_add(&bar[XB_TOPGEN], 1u);
;             else XB_SPIN(xb_ld(&bar[XB_TOPGEN]) == tg, bar);
;             __builtin_amdgcn_fence(__ATOMIC_ACQUIRE, "agent");
;             xb_add(&bar[XB_XGEN(b.x)], 1u);
;             asm volatile("s_waitcnt vmcnt(0)" ::: "memory");
;         } else {
;             XB_SPIN(xb_ld(&bar[XB_XGEN(b.x)]) == gen, bar);
;             __builtin_amdgcn_fence(__ATOMIC_ACQUIRE, "agent");
;             asm volatile("s_waitcnt vmcnt(0)" ::: "memory");
.LBB0_1634:
	s_or_b64 exec, exec, s[10:11]
	v_cvt_f32_u32_e32 v4, v2
	s_waitcnt vmcnt(0)
	v_readfirstlane_b32 s3, v3
	v_sub_u32_e32 v3, 0, v2
	v_rcp_iflag_f32_e32 v4, v4
	v_add_u32_e32 v5, s3, v1
	v_mul_f32_e32 v4, 0x4f7ffffe, v4
	v_cvt_u32_f32_e32 v4, v4
	v_mul_lo_u32 v1, v3, v4
	v_mul_hi_u32 v1, v4, v1
	v_add_u32_e32 v1, v4, v1
	v_mul_hi_u32 v1, v5, v1
	v_mul_lo_u32 v3, v1, v2
	v_sub_u32_e32 v3, v5, v3
	v_add_u32_e32 v4, 1, v1
	v_cmp_ge_u32_e32 vcc, v3, v2
	s_nop 1
	v_cndmask_b32_e32 v1, v1, v4, vcc
	v_sub_u32_e32 v4, v3, v2
	v_cndmask_b32_e32 v3, v3, v4, vcc
	v_add_u32_e32 v4, 1, v1
	v_cmp_ge_u32_e32 vcc, v3, v2
	v_add_u32_e32 v3, 1, v5
	s_nop 0
	v_cndmask_b32_e32 v1, v1, v4, vcc
	v_mul_lo_u32 v4, v2, v1
	v_add_u32_e32 v2, v4, v2
	v_cmp_ne_u32_e32 vcc, v3, v2
	s_and_saveexec_b64 s[8:9], vcc
	s_xor_b64 s[8:9], exec, s[8:9]
	s_cbranch_execz .LBB0_1648
	s_waitcnt lgkmcnt(0)
	s_add_u32 s20, s26, 0x7500
	s_addc_u32 s21, s27, 0
	v_mov_b32_e32 v0, 0
	global_load_dword v0, v0, s[20:21] sc1
	s_waitcnt vmcnt(0)
	v_cmp_eq_u32_e32 vcc, v0, v1
	s_and_saveexec_b64 s[10:11], vcc
	s_cbranch_execz .LBB0_1647
	s_add_u32 s18, s26, 0x4200
	s_addc_u32 s19, s27, 0
	s_mov_b32 s3, 1
	s_mov_b64 s[34:35], 0
	v_mov_b32_e32 v0, 0
	s_branch .LBB0_1638

; __device__ __forceinline__ unsigned xb_add(unsigned* p, unsigned v) { return __hip_atomic_fetch_add(p, v, __ATOMIC_RELAXED, __HIP_MEMORY_SCOPE_AGENT); }
; __device__ __forceinline__ void xcd_barrier(const XcdBarrier& b) {
;     ...
;             __builtin_amdgcn_fence(__ATOMIC_ACQUIRE, "agent");
;             xb_add(&bar[XB_XGEN(b.x)], 1u);
;             asm volatile("s_waitcnt vmcnt(0)" ::: "memory");
.LBB0_1665:
	s_or_b64 exec, exec, s[8:9]
	s_mov_b64 s[8:9], exec
	v_mbcnt_lo_u32_b32 v0, s8, 0
	v_mbcnt_hi_u32_b32 v0, s9, v0
	v_cmp_eq_u32_e32 vcc, 0, v0
	s_waitcnt vmcnt(0)
	buffer_inv sc1
	s_and_saveexec_b64 s[10:11], vcc
	s_cbranch_execz .LBB0_1667
	s_bcnt1_i32_b64 s3, s[8:9]
.LBB0_1667:
	s_or_b64 exec, exec, s[10:11]
	s_waitcnt vmcnt(0)
